# conversion split plus P0 W_in transposes moved to the 64 workgroups with the short S5-constants job
# speedup vs baseline: 1.0049x; 1.0006x over previous
.LBB0_179:
	s_lshl_b32 s82, s91, 3
	v_readlane_b32 s95, v254, 2
	s_lshl_b32 s70, s95, 3
	s_add_i32 s2, s3, s82
	s_mov_b32 s99, s70
	s_cmpk_lg_u32 s95, 0x100
	s_cbranch_scc1 .Ltr_go
	v_readlane_b32 s100, v254, 12
	s_nop 3
	s_movk_i32 s99, 0x200
	s_add_i32 s2, s100, 0xffffff40
	s_lshl_b32 s2, s2, 3
	s_add_i32 s2, s2, s3
	s_cmpk_lt_i32 s100, 0xc0
	s_cselect_b32 s2, 0x1000, s2
.Ltr_go:
	s_cmpk_gt_i32 s2, 0xfff
	s_waitcnt lgkmcnt(0)
	s_barrier
	s_cbranch_scc1 .LBB0_182
	s_load_dwordx2 s[0:1], s[42:43], 0x58
	s_lshl_b32 s3, s3, 14
	s_add_i32 s3, s3, 0
	v_and_b32_e32 v4, 0x7c, v134
	v_mov_b32_e32 v5, 0
	s_waitcnt lgkmcnt(0)
	v_lshl_add_u64 v[2:3], s[0:1], 0, v[4:5]
	v_add_u32_e32 v6, s3, v4
	v_lshlrev_b32_e32 v4, 3, v1
	v_lshrrev_b32_e32 v68, 5, v1
	v_and_b32_e32 v4, 56, v4
	v_mul_u32_u24_e32 v7, 0x84, v68
	v_lshrrev_b32_e32 v69, 3, v1
	v_mul_u32_u24_e32 v8, 0x84, v4
	v_bfe_u32 v9, v1, 3, 2
	v_lshrrev_b32_e32 v1, 2, v1
	v_lshlrev_b32_e32 v4, 1, v4
	v_and_or_b32 v1, v1, 8, v9
	v_lshl_add_u64 v[4:5], s[40:41], 0, v[4:5]
	s_mov_b64 s[0:1], 0x800000
	v_lshlrev_b32_e32 v9, 2, v69
	v_add_u32_e32 v73, v6, v7
	v_lshl_add_u64 v[4:5], v[4:5], 0, s[0:1]
	v_add3_u32 v70, s3, v8, v9
	v_or_b32_e32 v71, 8, v69
	v_or_b32_e32 v72, 4, v1
	s_lshl_b32 s3, s2, 5
	s_lshl_b32 s8, s99, 5
	s_movk_i32 s9, 0x7fff
	s_mov_b32 s10, 0xffff0000
	v_add_u32_e32 v74, 0x400, v73
	v_add_u32_e32 v75, 0x800, v73
	v_add_u32_e32 v76, 0xc00, v73
	v_add_u32_e32 v77, 0x1000, v73
	v_add_u32_e32 v79, 0x1400, v73
	v_add_u32_e32 v80, 0x1800, v73
	v_add_u32_e32 v81, 0x1c00, v73
.LBB0_181:
	s_ashr_i32 s0, s2, 31
	s_lshr_b32 s0, s0, 25
	s_add_i32 s0, s2, s0
	s_ashr_i32 s4, s0, 7
	s_and_b32 s0, s0, 0xffffff80
	s_lshl_b32 s11, s4, 12
	s_sub_i32 s1, s2, s0
	s_lshl_b32 s0, s4, 6
	s_sub_i32 s4, s3, s11
	v_or_b32_e32 v26, s0, v68
	s_cmp_lt_i32 s1, 64
	v_or_b32_e32 v10, 6, v26
	v_or_b32_e32 v12, 8, v26
	v_or_b32_e32 v14, 10, v26
	v_or_b32_e32 v16, 12, v26
	v_or_b32_e32 v18, 14, v26
	v_or_b32_e32 v20, 16, v26
	v_or_b32_e32 v28, 22, v26
	v_or_b32_e32 v30, 24, v26
	s_cselect_b64 s[6:7], -1, 0
	s_bitcmp0_b32 s1, 0
	v_ashrrev_i32_e32 v27, 31, v26
	v_or_b32_e32 v6, 2, v26
	v_or_b32_e32 v8, 4, v26
	v_or_b32_e32 v22, 18, v26
	v_or_b32_e32 v24, 20, v26
	v_or_b32_e32 v32, 26, v26
	v_or_b32_e32 v34, 28, v26
	v_or_b32_e32 v36, 30, v26
	v_or_b32_e32 v38, 32, v26
	v_or_b32_e32 v40, 34, v26
	v_or_b32_e32 v42, 36, v26
	v_or_b32_e32 v44, 38, v26
	v_or_b32_e32 v46, 40, v26
	v_or_b32_e32 v48, 42, v26
	v_or_b32_e32 v50, 44, v26
	v_or_b32_e32 v52, 46, v26
	v_or_b32_e32 v54, 48, v26
	v_or_b32_e32 v56, 50, v26
	v_or_b32_e32 v58, 52, v26
	v_or_b32_e32 v60, 54, v26
	v_or_b32_e32 v62, 56, v26
	v_or_b32_e32 v64, 58, v26
	v_or_b32_e32 v66, 60, v26
	v_or_b32_e32 v82, 62, v26
	v_ashrrev_i32_e32 v11, 31, v10
	v_ashrrev_i32_e32 v13, 31, v12
	v_ashrrev_i32_e32 v15, 31, v14
	v_ashrrev_i32_e32 v17, 31, v16
	v_ashrrev_i32_e32 v19, 31, v18
	v_ashrrev_i32_e32 v21, 31, v20
	v_ashrrev_i32_e32 v29, 31, v28
	v_ashrrev_i32_e32 v31, 31, v30
	s_cselect_b64 s[12:13], -1, 0
	s_ashr_i32 s5, s4, 31
	v_lshlrev_b64 v[26:27], 14, v[26:27]
	v_ashrrev_i32_e32 v7, 31, v6
	v_ashrrev_i32_e32 v9, 31, v8
	v_ashrrev_i32_e32 v23, 31, v22
	v_ashrrev_i32_e32 v25, 31, v24
	v_ashrrev_i32_e32 v33, 31, v32
	v_ashrrev_i32_e32 v35, 31, v34
	v_ashrrev_i32_e32 v37, 31, v36
	v_ashrrev_i32_e32 v39, 31, v38
	v_ashrrev_i32_e32 v41, 31, v40
	v_ashrrev_i32_e32 v43, 31, v42
	v_ashrrev_i32_e32 v45, 31, v44
	v_ashrrev_i32_e32 v47, 31, v46
	v_ashrrev_i32_e32 v49, 31, v48
	v_ashrrev_i32_e32 v51, 31, v50
	v_ashrrev_i32_e32 v53, 31, v52
	v_ashrrev_i32_e32 v55, 31, v54
	v_ashrrev_i32_e32 v57, 31, v56
	v_ashrrev_i32_e32 v59, 31, v58
	v_ashrrev_i32_e32 v61, 31, v60
	v_ashrrev_i32_e32 v63, 31, v62
	v_ashrrev_i32_e32 v65, 31, v64
	v_ashrrev_i32_e32 v67, 31, v66
	v_ashrrev_i32_e32 v83, 31, v82
	v_lshlrev_b64 v[10:11], 14, v[10:11]
	v_lshlrev_b64 v[12:13], 14, v[12:13]
	v_lshlrev_b64 v[14:15], 14, v[14:15]
	v_lshlrev_b64 v[16:17], 14, v[16:17]
	v_lshlrev_b64 v[18:19], 14, v[18:19]
	v_lshlrev_b64 v[20:21], 14, v[20:21]
	v_lshlrev_b64 v[28:29], 14, v[28:29]
	v_lshlrev_b64 v[30:31], 14, v[30:31]
	v_lshl_add_u64 v[88:89], s[4:5], 2, v[2:3]
	s_and_b64 vcc, s[6:7], s[12:13]
	v_lshlrev_b64 v[6:7], 14, v[6:7]
	v_lshlrev_b64 v[8:9], 14, v[8:9]
	v_lshlrev_b64 v[22:23], 14, v[22:23]
	v_lshlrev_b64 v[24:25], 14, v[24:25]
	v_lshlrev_b64 v[32:33], 14, v[32:33]
	v_lshlrev_b64 v[34:35], 14, v[34:35]
	v_lshlrev_b64 v[36:37], 14, v[36:37]
	v_lshlrev_b64 v[38:39], 14, v[38:39]
	v_lshlrev_b64 v[40:41], 14, v[40:41]
	v_lshlrev_b64 v[42:43], 14, v[42:43]
	v_lshlrev_b64 v[44:45], 14, v[44:45]
	v_lshlrev_b64 v[46:47], 14, v[46:47]
	v_lshlrev_b64 v[48:49], 14, v[48:49]
	v_lshlrev_b64 v[50:51], 14, v[50:51]
	v_lshlrev_b64 v[52:53], 14, v[52:53]
	v_lshlrev_b64 v[54:55], 14, v[54:55]
	v_lshlrev_b64 v[56:57], 14, v[56:57]
	v_lshlrev_b64 v[58:59], 14, v[58:59]
	v_lshlrev_b64 v[60:61], 14, v[60:61]
	v_lshlrev_b64 v[62:63], 14, v[62:63]
	v_lshlrev_b64 v[64:65], 14, v[64:65]
	v_lshlrev_b64 v[66:67], 14, v[66:67]
	v_lshlrev_b64 v[82:83], 14, v[82:83]
	v_cndmask_b32_e32 v92, v69, v1, vcc
	v_lshl_add_u64 v[26:27], v[88:89], 0, v[26:27]
	v_lshl_add_u64 v[10:11], v[88:89], 0, v[10:11]
	v_lshl_add_u64 v[12:13], v[88:89], 0, v[12:13]
	v_lshl_add_u64 v[14:15], v[88:89], 0, v[14:15]
	v_lshl_add_u64 v[16:17], v[88:89], 0, v[16:17]
	v_lshl_add_u64 v[18:19], v[88:89], 0, v[18:19]
	v_lshl_add_u64 v[20:21], v[88:89], 0, v[20:21]
	v_lshl_add_u64 v[28:29], v[88:89], 0, v[28:29]
	v_lshl_add_u64 v[30:31], v[88:89], 0, v[30:31]
	v_lshl_add_u64 v[6:7], v[88:89], 0, v[6:7]
	v_lshl_add_u64 v[8:9], v[88:89], 0, v[8:9]
	v_lshl_add_u64 v[22:23], v[88:89], 0, v[22:23]
	v_lshl_add_u64 v[24:25], v[88:89], 0, v[24:25]
	v_lshl_add_u64 v[32:33], v[88:89], 0, v[32:33]
	v_lshl_add_u64 v[34:35], v[88:89], 0, v[34:35]
	v_lshl_add_u64 v[36:37], v[88:89], 0, v[36:37]
	v_lshl_add_u64 v[38:39], v[88:89], 0, v[38:39]
	v_lshl_add_u64 v[40:41], v[88:89], 0, v[40:41]
	v_lshl_add_u64 v[42:43], v[88:89], 0, v[42:43]
	v_lshl_add_u64 v[44:45], v[88:89], 0, v[44:45]
	v_lshl_add_u64 v[46:47], v[88:89], 0, v[46:47]
	v_lshl_add_u64 v[48:49], v[88:89], 0, v[48:49]
	v_lshl_add_u64 v[50:51], v[88:89], 0, v[50:51]
	v_lshl_add_u64 v[52:53], v[88:89], 0, v[52:53]
	v_lshl_add_u64 v[54:55], v[88:89], 0, v[54:55]
	v_lshl_add_u64 v[56:57], v[88:89], 0, v[56:57]
	v_lshl_add_u64 v[58:59], v[88:89], 0, v[58:59]
	v_lshl_add_u64 v[60:61], v[88:89], 0, v[60:61]
	v_lshl_add_u64 v[62:63], v[88:89], 0, v[62:63]
	v_lshl_add_u64 v[64:65], v[88:89], 0, v[64:65]
	v_lshl_add_u64 v[66:67], v[88:89], 0, v[66:67]
	v_lshl_add_u64 v[82:83], v[88:89], 0, v[82:83]
	v_subrev_u32_e32 v88, s11, v92
	global_load_dword v92, v[26:27], off nt
	global_load_dword v93, v[6:7], off nt
	global_load_dword v94, v[8:9], off nt
	global_load_dword v95, v[10:11], off nt
	global_load_dword v96, v[12:13], off nt
	global_load_dword v97, v[14:15], off nt
	global_load_dword v98, v[16:17], off nt
	global_load_dword v99, v[18:19], off nt
	global_load_dword v100, v[20:21], off nt
	global_load_dword v101, v[22:23], off nt
	global_load_dword v102, v[24:25], off nt
	global_load_dword v103, v[28:29], off nt
	global_load_dword v104, v[30:31], off nt
	global_load_dword v105, v[32:33], off nt
	global_load_dword v106, v[34:35], off nt
	global_load_dword v10, v[36:37], off nt
	global_load_dword v11, v[38:39], off nt
	global_load_dword v12, v[40:41], off nt
	global_load_dword v13, v[42:43], off nt
	global_load_dword v14, v[44:45], off nt
	global_load_dword v15, v[46:47], off nt
	global_load_dword v16, v[48:49], off nt
	global_load_dword v17, v[50:51], off nt
	global_load_dword v18, v[52:53], off nt
	global_load_dword v19, v[54:55], off nt
	global_load_dword v20, v[56:57], off nt
	global_load_dword v21, v[58:59], off nt
	global_load_dword v26, v[60:61], off nt
	global_load_dword v27, v[62:63], off nt
	global_load_dword v28, v[64:65], off nt
	global_load_dword v29, v[66:67], off nt
	global_load_dword v30, v[82:83], off nt
	v_cndmask_b32_e32 v89, v71, v72, vcc
	v_add_u32_e32 v6, s3, v88
	v_subrev_u32_e32 v8, s11, v89
	s_ashr_i32 s1, s0, 31
	v_ashrrev_i32_e32 v7, 31, v6
	v_add_u32_e32 v8, s3, v8
	s_waitcnt vmcnt(30)
	ds_write2_b32 v73, v92, v93 offset1:66
	s_waitcnt vmcnt(28)
	ds_write2_b32 v73, v94, v95 offset0:132 offset1:198
	s_waitcnt vmcnt(26)
	ds_write2_b32 v74, v96, v97 offset0:8 offset1:74
	s_waitcnt vmcnt(24)
	ds_write2_b32 v74, v98, v99 offset0:140 offset1:206
	s_waitcnt vmcnt(22)
	ds_write2_b32 v75, v100, v101 offset0:16 offset1:82
	s_waitcnt vmcnt(20)
	ds_write2_b32 v75, v102, v103 offset0:148 offset1:214
	s_waitcnt vmcnt(18)
	ds_write2_b32 v76, v104, v105 offset0:24 offset1:90
	s_waitcnt vmcnt(16)
	ds_write2_b32 v76, v106, v10 offset0:156 offset1:222
	s_waitcnt vmcnt(14)
	ds_write2_b32 v77, v11, v12 offset0:32 offset1:98
	s_waitcnt vmcnt(12)
	ds_write2_b32 v77, v13, v14 offset0:164 offset1:230
	s_waitcnt vmcnt(10)
	ds_write2_b32 v79, v15, v16 offset0:40 offset1:106
	s_waitcnt vmcnt(8)
	ds_write2_b32 v79, v17, v18 offset0:172 offset1:238
	s_waitcnt vmcnt(6)
	ds_write2_b32 v80, v19, v20 offset0:48 offset1:114
	s_waitcnt vmcnt(4)
	ds_write2_b32 v80, v21, v26 offset0:180 offset1:246
	s_waitcnt vmcnt(2)
	ds_write2_b32 v81, v27, v28 offset0:56 offset1:122
	s_waitcnt vmcnt(0)
	ds_write2_b32 v81, v29, v30 offset0:188 offset1:254
	v_lshl_add_u64 v[90:91], s[0:1], 1, v[4:5]
	v_lshlrev_b64 v[6:7], 12, v[6:7]
	v_ashrrev_i32_e32 v9, 31, v8
	s_waitcnt lgkmcnt(0)
	v_lshl_add_u64 v[22:23], v[90:91], 0, v[6:7]
	v_lshlrev_b64 v[6:7], 12, v[8:9]
	v_add_u32_e32 v85, s4, v69
	v_lshl_add_u64 v[24:25], v[90:91], 0, v[6:7]
	ds_read2_b32 v[6:7], v70 offset0:33 offset1:41
	ds_read2_b32 v[8:9], v70 offset1:8
	ds_read2_b32 v[10:11], v70 offset0:66 offset1:74
	ds_read2_b32 v[12:13], v70 offset0:99 offset1:107
	ds_read2_b32 v[14:15], v70 offset0:132 offset1:140
	ds_read2_b32 v[16:17], v70 offset0:165 offset1:173
	ds_read2_b32 v[18:19], v70 offset0:198 offset1:206
	ds_read2_b32 v[20:21], v70 offset0:231 offset1:239
	ds_read2_b32 v[26:27], v70 offset0:49 offset1:57
	ds_read2_b32 v[28:29], v70 offset0:16 offset1:24
	ds_read2_b32 v[30:31], v70 offset0:82 offset1:90
	ds_read2_b32 v[32:33], v70 offset0:115 offset1:123
	ds_read2_b32 v[34:35], v70 offset0:148 offset1:156
	ds_read2_b32 v[36:37], v70 offset0:181 offset1:189
	ds_read2_b32 v[38:39], v70 offset0:214 offset1:222
	ds_read2_b32 v[40:41], v70 offset0:247 offset1:255
	v_add_u32_e32 v84, 16, v85
	v_add_u32_e32 v86, 24, v85
	v_ashrrev_i32_e32 v85, 31, v84
	v_ashrrev_i32_e32 v87, 31, v86
	v_lshlrev_b64 v[84:85], 12, v[84:85]
	v_lshlrev_b64 v[86:87], 12, v[86:87]
	s_waitcnt lgkmcnt(14)
	v_bfe_u32 v42, v8, 16, 1
	s_waitcnt lgkmcnt(13)
	v_bfe_u32 v44, v10, 16, 1
	s_waitcnt lgkmcnt(11)
	v_bfe_u32 v46, v14, 16, 1
	s_waitcnt lgkmcnt(9)
	v_bfe_u32 v48, v18, 16, 1
	v_lshl_add_u64 v[84:85], v[90:91], 0, v[84:85]
	v_lshl_add_u64 v[86:87], v[90:91], 0, v[86:87]
	v_bfe_u32 v43, v6, 16, 1
	v_bfe_u32 v45, v12, 16, 1
	v_bfe_u32 v47, v16, 16, 1
	s_waitcnt lgkmcnt(8)
	v_bfe_u32 v49, v20, 16, 1
	v_bfe_u32 v50, v9, 16, 1
	v_bfe_u32 v51, v7, 16, 1
	v_bfe_u32 v52, v11, 16, 1
	v_bfe_u32 v53, v13, 16, 1
	v_bfe_u32 v54, v15, 16, 1
	v_bfe_u32 v55, v17, 16, 1
	v_bfe_u32 v56, v19, 16, 1
	v_bfe_u32 v57, v21, 16, 1
	s_waitcnt lgkmcnt(6)
	v_bfe_u32 v58, v28, 16, 1
	s_waitcnt lgkmcnt(5)
	v_bfe_u32 v60, v30, 16, 1
	s_waitcnt lgkmcnt(4)
	v_bfe_u32 v61, v32, 16, 1
	s_waitcnt lgkmcnt(3)
	v_bfe_u32 v62, v34, 16, 1
	s_waitcnt lgkmcnt(2)
	v_bfe_u32 v63, v36, 16, 1
	s_waitcnt lgkmcnt(1)
	v_bfe_u32 v64, v38, 16, 1
	v_bfe_u32 v66, v29, 16, 1
	v_bfe_u32 v82, v31, 16, 1
	v_bfe_u32 v88, v35, 16, 1
	v_bfe_u32 v90, v39, 16, 1
	v_add3_u32 v8, v8, v42, s9
	v_add3_u32 v10, v10, v44, s9
	v_add3_u32 v14, v14, v46, s9
	v_add3_u32 v18, v18, v48, s9
	v_bfe_u32 v59, v26, 16, 1
	s_waitcnt lgkmcnt(0)
	v_bfe_u32 v65, v40, 16, 1
	v_bfe_u32 v67, v27, 16, 1
	v_bfe_u32 v83, v33, 16, 1
	v_bfe_u32 v89, v37, 16, 1
	v_bfe_u32 v91, v41, 16, 1
	v_add3_u32 v6, v6, v43, s9
	v_add3_u32 v12, v12, v45, s9
	v_add3_u32 v16, v16, v47, s9
	v_add3_u32 v20, v20, v49, s9
	v_add3_u32 v9, v9, v50, s9
	v_add3_u32 v42, v7, v51, s9
	v_add3_u32 v7, v11, v52, s9
	v_add3_u32 v11, v13, v53, s9
	v_add3_u32 v13, v15, v54, s9
	v_add3_u32 v15, v17, v55, s9
	v_add3_u32 v17, v19, v56, s9
	v_add3_u32 v19, v21, v57, s9
	v_add3_u32 v21, v28, v58, s9
	v_add3_u32 v28, v30, v60, s9
	v_add3_u32 v30, v32, v61, s9
	v_add3_u32 v32, v34, v62, s9
	v_add3_u32 v34, v36, v63, s9
	v_add3_u32 v36, v38, v64, s9
	v_add3_u32 v29, v29, v66, s9
	v_add3_u32 v31, v31, v82, s9
	v_add3_u32 v35, v35, v88, s9
	v_add3_u32 v39, v39, v90, s9
	v_lshrrev_b32_e32 v8, 16, v8
	v_lshrrev_b32_e32 v10, 16, v10
	v_lshrrev_b32_e32 v14, 16, v14
	v_lshrrev_b32_e32 v18, 16, v18
	v_add3_u32 v26, v26, v59, s9
	v_add3_u32 v38, v40, v65, s9
	v_add3_u32 v27, v27, v67, s9
	v_add3_u32 v33, v33, v83, s9
	v_add3_u32 v37, v37, v89, s9
	v_add3_u32 v40, v41, v91, s9
	v_lshrrev_b32_e32 v41, 16, v9
	v_lshrrev_b32_e32 v43, 16, v7
	v_lshrrev_b32_e32 v13, 16, v13
	v_lshrrev_b32_e32 v17, 16, v17
	v_lshrrev_b32_e32 v21, 16, v21
	v_lshrrev_b32_e32 v28, 16, v28
	v_lshrrev_b32_e32 v32, 16, v32
	v_lshrrev_b32_e32 v36, 16, v36
	v_lshrrev_b32_e32 v29, 16, v29
	v_lshrrev_b32_e32 v31, 16, v31
	v_lshrrev_b32_e32 v35, 16, v35
	v_lshrrev_b32_e32 v39, 16, v39
	v_and_or_b32 v6, v6, s10, v8
	v_and_or_b32 v7, v12, s10, v10
	v_and_or_b32 v8, v16, s10, v14
	v_and_or_b32 v9, v20, s10, v18
	v_and_or_b32 v10, v42, s10, v41
	v_and_or_b32 v11, v11, s10, v43
	v_and_or_b32 v12, v15, s10, v13
	v_and_or_b32 v13, v19, s10, v17
	v_and_or_b32 v14, v26, s10, v21
	v_and_or_b32 v15, v30, s10, v28
	v_and_or_b32 v16, v34, s10, v32
	v_and_or_b32 v17, v38, s10, v36
	v_and_or_b32 v18, v27, s10, v29
	v_and_or_b32 v19, v33, s10, v31
	v_and_or_b32 v20, v37, s10, v35
	v_and_or_b32 v21, v40, s10, v39
	global_store_dwordx4 v[22:23], v[6:9], off
	global_store_dwordx4 v[24:25], v[10:13], off
	global_store_dwordx4 v[84:85], v[14:17], off
	global_store_dwordx4 v[86:87], v[18:21], off
	s_waitcnt lgkmcnt(0)
	s_add_i32 s2, s2, s99
	s_add_i32 s3, s3, s8
	s_cmpk_gt_i32 s2, 0xfff
	s_cbranch_scc0 .LBB0_181
